# residual epilogue de-serialised (default-policy xs stores) + MIDK ssq loads batched + attention Q-load vmcnt ladder removed
# speedup vs baseline: 1.0108x; 1.0108x over previous
; #define PG8_GAS __attribute__((address_space(1)))
; template <class T> __device__ __forceinline__ GAS T* gp(T* p) { return (GAS T*)p; }
;     __device__ __forceinline__ void operator()(const f32x4 (&acc)[2][2][4][2], const Unit& u, int wr, int wc, int fr, int fq) const {
;         const int b = (u.pm * BM) >> 13;
;         const float* gp = mod + b * 9216 + step * 3072 + 2048; const float coef = step == 1 ? 1.0f : 0.5f;
;         const float* basef = step == 0 ? xin : (const float*)nullptr; const bf16_t* baseb = xs; bf16_t* out = xs;
;         const int col0 = u.pn * BM + wc * 32 + 8 * fq;
;         f32x4 gv[2][2];
; #pragma unroll
;         for (int bj = 0; bj < 2; ++bj)
; #pragma unroll
;             for (int n = 0; n < 2; ++n) gv[bj][n] = (*(const PG8_GAS f32x4*)(gp + col0 + bj * HALF + 4 * n) + 1.0f) * coef;
; #pragma unroll
;         for (int ai = 0; ai < 2; ++ai)
; #pragma unroll
;             for (int m = 0; m < 4; ++m) {
;                 const size_t off = (size_t)(u.pm * BM + ai * HALF + wr * 64 + m * 16 + fr) * 1024 + col0;
; #pragma unroll
;                 for (int bj = 0; bj < 2; ++bj) {
;                     f32x4 b0, b1;
;                     if (basef) { b0 = __builtin_nontemporal_load((const PG8_GAS f32x4*)(basef + off + bj * HALF)); b1 = __builtin_nontemporal_load((const PG8_GAS f32x4*)(basef + off + bj * HALF + 4)); }
;                     else { const u32x4 w = __builtin_nontemporal_load((const PG8_GAS u32x4*)(baseb + off + bj * HALF));
;                         b0 = (f32x4){__uint_as_float(w.x << 16), __uint_as_float(w.x & 0xffff0000u), __uint_as_float(w.y << 16), __uint_as_float(w.y & 0xffff0000u)};
;                         b1 = (f32x4){__uint_as_float(w.z << 16), __uint_as_float(w.z & 0xffff0000u), __uint_as_float(w.w << 16), __uint_as_float(w.w & 0xffff0000u)}; }
;                     const f32x4 o0 = b0 + gv[bj][0] * acc[ai][bj][m][0], o1 = b1 + gv[bj][1] * acc[ai][bj][m][1];
.LBB0_628:
	s_lshr_b32 s4, s25, 5
	s_mulk_i32 s4, 0x2400
	s_ashr_i32 s5, s4, 31
	s_lshl_b64 s[4:5], s[4:5], 2
	s_add_u32 s4, s38, s4
	v_lshl_or_b32 v2, s40, 8, v178
	s_addc_u32 s5, s18, s5
	v_ashrrev_i32_e32 v3, 31, v2
	v_lshl_add_u64 v[134:135], v[2:3], 2, s[4:5]
	s_mov_b64 s[4:5], 0x2000
	v_lshl_add_u64 v[138:139], v[134:135], 0, s[4:5]
	v_add_co_u32_e32 v134, vcc, s47, v134
	v_add_u32_e32 v170, s42, v176
	s_nop 0
	v_addc_co_u32_e32 v135, vcc, 0, v135, vcc
	global_load_dwordx4 v[146:149], v[134:135], off
	s_nop 0
	global_load_dwordx4 v[134:137], v[138:139], off offset:528
	global_load_dwordx4 v[142:145], v[138:139], off offset:16
	s_nop 0
	global_load_dwordx4 v[138:141], v[138:139], off offset:512
	v_ashrrev_i32_e32 v171, 31, v170
	v_lshlrev_b64 v[150:151], 10, v[170:171]
	v_lshl_add_u64 v[150:151], v[150:151], 0, v[2:3]
	v_lshl_add_u64 v[2:3], v[150:151], 1, s[56:57]
	v_lshl_add_u64 v[174:175], v[150:151], 2, s[64:65]
	v_mov_b64_e32 v[182:183], v[2:3]
	s_andn2_b64 vcc, exec, s[66:67]
	s_cbranch_vccnz .Lres_epi_bf16
	s_mov_b32 s4, 0x10000
	s_mov_b32 s5, 0
	s_mov_b32 vcc_lo, 0x50000
	s_mov_b32 vcc_hi, 0
	global_load_dwordx4 v[150:153], v[174:175], off nt
	global_load_dwordx4 v[154:157], v[174:175], off offset:16 nt
	global_load_dwordx4 v[170:173], v[174:175], off offset:512 nt
	global_load_dwordx4 v[184:187], v[174:175], off offset:528 nt
	v_lshl_add_u64 v[174:175], v[174:175], 0, s[4:5]
	global_load_dwordx4 v[188:191], v[174:175], off nt
	global_load_dwordx4 v[192:195], v[174:175], off offset:16 nt
	global_load_dwordx4 v[208:211], v[174:175], off offset:512 nt
	global_load_dwordx4 v[226:229], v[174:175], off offset:528 nt
	v_lshl_add_u64 v[174:175], v[174:175], 0, s[4:5]
	global_load_dwordx4 v[230:233], v[174:175], off nt
	global_load_dwordx4 v[234:237], v[174:175], off offset:16 nt
	global_load_dwordx4 v[238:241], v[174:175], off offset:512 nt
	global_load_dwordx4 v[242:245], v[174:175], off offset:528 nt
	v_lshl_add_u64 v[174:175], v[174:175], 0, s[4:5]
	global_load_dwordx4 v[246:249], v[174:175], off nt
	global_load_dwordx4 v[250:253], v[174:175], off offset:16 nt
	s_waitcnt vmcnt(12)
	v_pk_add_f32 v[148:149], v[148:149], 1.0 op_sel_hi:[1,0]
	v_pk_add_f32 v[180:181], v[146:147], 1.0 op_sel_hi:[1,0]
	v_pk_mul_f32 v[146:147], s[60:61], v[148:149]
	v_pk_mul_f32 v[148:149], s[10:11], v[180:181]
	v_pk_add_f32 v[180:181], v[142:143], 1.0 op_sel_hi:[1,0]
	v_pk_add_f32 v[142:143], v[144:145], 1.0 op_sel_hi:[1,0]
	v_pk_mul_f32 v[144:145], s[10:11], v[180:181]
	v_pk_mul_f32 v[142:143], s[60:61], v[142:143]
	v_pk_add_f32 v[140:141], v[140:141], 1.0 op_sel_hi:[1,0]
	v_pk_add_f32 v[180:181], v[138:139], 1.0 op_sel_hi:[1,0]
	v_pk_mul_f32 v[138:139], s[60:61], v[140:141]
	v_pk_mul_f32 v[140:141], s[10:11], v[180:181]
	v_pk_add_f32 v[180:181], v[134:135], 1.0 op_sel_hi:[1,0]
	v_pk_add_f32 v[134:135], v[136:137], 1.0 op_sel_hi:[1,0]
	v_pk_mul_f32 v[136:137], s[10:11], v[180:181]
	v_pk_mul_f32 v[134:135], s[60:61], v[134:135]
	v_pk_fma_f32 v[130:131], v[130:131], v[148:149], v[150:151]
	v_pk_fma_f32 v[132:133], v[132:133], v[146:147], v[152:153]
	v_pk_fma_f32 v[126:127], v[126:127], v[144:145], v[154:155]
	v_pk_fma_f32 v[128:129], v[128:129], v[142:143], v[156:157]
	v_cvt_pk_bf16_f32 v130, v130, v131
	v_cvt_pk_bf16_f32 v131, v132, v133
	v_cvt_pk_bf16_f32 v132, v126, v127
	v_cvt_pk_bf16_f32 v133, v128, v129
	global_load_dwordx4 v[150:153], v[174:175], off offset:512 nt
	global_load_dwordx4 v[154:157], v[174:175], off offset:528 nt
	v_lshl_add_u64 v[174:175], v[174:175], 0, vcc
	s_waitcnt vmcnt(12)
	v_pk_fma_f32 v[122:123], v[122:123], v[140:141], v[170:171]
	v_pk_fma_f32 v[124:125], v[124:125], v[138:139], v[172:173]
	v_pk_fma_f32 v[118:119], v[118:119], v[136:137], v[184:185]
	v_pk_fma_f32 v[120:121], v[120:121], v[134:135], v[186:187]
	v_cvt_pk_bf16_f32 v122, v122, v123
	v_cvt_pk_bf16_f32 v123, v124, v125
	v_cvt_pk_bf16_f32 v124, v118, v119
	v_cvt_pk_bf16_f32 v125, v120, v121
	global_load_dwordx4 v[126:129], v[174:175], off nt
	global_load_dwordx4 v[170:173], v[174:175], off offset:16 nt
	global_load_dwordx4 v[184:187], v[174:175], off offset:512 nt
	global_load_dwordx4 v[118:121], v[174:175], off offset:528 nt
	v_lshl_add_u64 v[174:175], v[174:175], 0, s[4:5]
	s_waitcnt vmcnt(14)
	v_pk_fma_f32 v[114:115], v[114:115], v[148:149], v[188:189]
	v_pk_fma_f32 v[116:117], v[116:117], v[146:147], v[190:191]
	v_pk_fma_f32 v[110:111], v[110:111], v[144:145], v[192:193]
	v_pk_fma_f32 v[112:113], v[112:113], v[142:143], v[194:195]
	v_cvt_pk_bf16_f32 v114, v114, v115
	v_cvt_pk_bf16_f32 v115, v116, v117
	v_cvt_pk_bf16_f32 v116, v110, v111
	v_cvt_pk_bf16_f32 v117, v112, v113
	global_load_dwordx4 v[188:191], v[174:175], off nt
	global_load_dwordx4 v[192:195], v[174:175], off offset:16 nt
	s_waitcnt vmcnt(14)
	v_pk_fma_f32 v[106:107], v[106:107], v[140:141], v[208:209]
	v_pk_fma_f32 v[108:109], v[108:109], v[138:139], v[210:211]
	v_pk_fma_f32 v[102:103], v[102:103], v[136:137], v[226:227]
	v_pk_fma_f32 v[104:105], v[104:105], v[134:135], v[228:229]
	v_cvt_pk_bf16_f32 v106, v106, v107
	v_cvt_pk_bf16_f32 v107, v108, v109
	v_cvt_pk_bf16_f32 v108, v102, v103
	v_cvt_pk_bf16_f32 v109, v104, v105
	global_load_dwordx4 v[110:113], v[174:175], off offset:512 nt
	global_load_dwordx4 v[208:211], v[174:175], off offset:528 nt
	v_lshl_add_u64 v[174:175], v[174:175], 0, s[4:5]
	global_load_dwordx4 v[226:229], v[174:175], off nt
	global_load_dwordx4 v[102:105], v[174:175], off offset:16 nt
	s_waitcnt vmcnt(16)
; #define PG8_GAS __attribute__((address_space(1)))
; __device__ __forceinline__ unsigned cvtpk(float lo, float hi) { f32x2 v = {lo, hi}; bf16x2_t b = __builtin_convertvector(v, bf16x2_t); return __builtin_bit_cast(unsigned, b); }
;     __device__ __forceinline__ void operator()(const f32x4 (&acc)[2][2][4][2], const Unit& u, int wr, int wc, int fr, int fq) const {
;     ...
;         for (int ai = 0; ai < 2; ++ai)
; #pragma unroll
;             for (int m = 0; m < 4; ++m) {
;                 const size_t off = (size_t)(u.pm * BM + ai * HALF + wr * 64 + m * 16 + fr) * 1024 + col0;
; #pragma unroll
;                 for (int bj = 0; bj < 2; ++bj) {
;                     f32x4 b0, b1;
;                     if (basef) { b0 = __builtin_nontemporal_load((const PG8_GAS f32x4*)(basef + off + bj * HALF)); b1 = __builtin_nontemporal_load((const PG8_GAS f32x4*)(basef + off + bj * HALF + 4)); }
;                     else { const u32x4 w = __builtin_nontemporal_load((const PG8_GAS u32x4*)(baseb + off + bj * HALF));
;                         b0 = (f32x4){__uint_as_float(w.x << 16), __uint_as_float(w.x & 0xffff0000u), __uint_as_float(w.y << 16), __uint_as_float(w.y & 0xffff0000u)};
;                         b1 = (f32x4){__uint_as_float(w.z << 16), __uint_as_float(w.z & 0xffff0000u), __uint_as_float(w.w << 16), __uint_as_float(w.w & 0xffff0000u)}; }
;                     const f32x4 o0 = b0 + gv[bj][0] * acc[ai][bj][m][0], o1 = b1 + gv[bj][1] * acc[ai][bj][m][1];
;                     u32x4 w; w.x = cvtpk(o0[0], o0[1]); w.y = cvtpk(o0[2], o0[3]); w.z = cvtpk(o1[0], o1[1]); w.w = cvtpk(o1[2], o1[3]);
;                     __builtin_nontemporal_store(w, (PG8_GAS u32x4*)(out + off + bj * HALF));
;                 }
	v_pk_fma_f32 v[98:99], v[98:99], v[148:149], v[230:231]
	v_pk_fma_f32 v[100:101], v[100:101], v[146:147], v[232:233]
	v_pk_fma_f32 v[94:95], v[94:95], v[144:145], v[234:235]
	v_pk_fma_f32 v[96:97], v[96:97], v[142:143], v[236:237]
	v_cvt_pk_bf16_f32 v98, v98, v99
	v_cvt_pk_bf16_f32 v99, v100, v101
	v_cvt_pk_bf16_f32 v100, v94, v95
	v_cvt_pk_bf16_f32 v101, v96, v97
	global_load_dwordx4 v[230:233], v[174:175], off offset:512 nt
	global_load_dwordx4 v[234:237], v[174:175], off offset:528 nt
	v_lshl_add_u64 v[174:175], v[174:175], 0, s[4:5]
	s_waitcnt vmcnt(16)
	v_pk_fma_f32 v[90:91], v[90:91], v[140:141], v[238:239]
	v_pk_fma_f32 v[92:93], v[92:93], v[138:139], v[240:241]
	v_pk_fma_f32 v[86:87], v[86:87], v[136:137], v[242:243]
	v_pk_fma_f32 v[88:89], v[88:89], v[134:135], v[244:245]
	v_cvt_pk_bf16_f32 v90, v90, v91
	v_cvt_pk_bf16_f32 v91, v92, v93
	v_cvt_pk_bf16_f32 v92, v86, v87
	v_cvt_pk_bf16_f32 v93, v88, v89
	global_load_dwordx4 v[94:97], v[174:175], off nt
	global_load_dwordx4 v[238:241], v[174:175], off offset:16 nt
	global_load_dwordx4 v[242:245], v[174:175], off offset:512 nt
	global_load_dwordx4 v[86:89], v[174:175], off offset:528 nt
	s_mov_b32 s4, 0x8000
	s_mov_b32 vcc_lo, 0x28000
	global_store_dwordx4 v[2:3], v[130:133], off
	global_store_dwordx4 v[2:3], v[122:125], off offset:256
	v_lshl_add_u64 v[2:3], v[2:3], 0, s[4:5]
	global_store_dwordx4 v[2:3], v[114:117], off
	global_store_dwordx4 v[2:3], v[106:109], off offset:256
	v_lshl_add_u64 v[2:3], v[2:3], 0, s[4:5]
	global_store_dwordx4 v[2:3], v[98:101], off
	global_store_dwordx4 v[2:3], v[90:93], off offset:256
	v_lshl_add_u64 v[2:3], v[2:3], 0, s[4:5]
	s_waitcnt vmcnt(24)
	v_pk_fma_f32 v[82:83], v[82:83], v[148:149], v[246:247]
	v_pk_fma_f32 v[84:85], v[84:85], v[146:147], v[248:249]
	v_pk_fma_f32 v[78:79], v[78:79], v[144:145], v[250:251]
	v_pk_fma_f32 v[80:81], v[80:81], v[142:143], v[252:253]
	v_cvt_pk_bf16_f32 v82, v82, v83
	v_cvt_pk_bf16_f32 v83, v84, v85
	v_cvt_pk_bf16_f32 v84, v78, v79
	v_cvt_pk_bf16_f32 v85, v80, v81
	global_store_dwordx4 v[2:3], v[82:85], off
	s_waitcnt vmcnt(23)
	v_pk_fma_f32 v[74:75], v[74:75], v[140:141], v[150:151]
	v_pk_fma_f32 v[76:77], v[76:77], v[138:139], v[152:153]
	v_pk_fma_f32 v[70:71], v[70:71], v[136:137], v[154:155]
	v_pk_fma_f32 v[72:73], v[72:73], v[134:135], v[156:157]
	v_cvt_pk_bf16_f32 v74, v74, v75
	v_cvt_pk_bf16_f32 v75, v76, v77
	v_cvt_pk_bf16_f32 v76, v70, v71
	v_cvt_pk_bf16_f32 v77, v72, v73
	global_store_dwordx4 v[2:3], v[74:77], off offset:256
	v_lshl_add_u64 v[2:3], v[2:3], 0, vcc
	s_waitcnt vmcnt(22)
	v_pk_fma_f32 v[66:67], v[66:67], v[148:149], v[126:127]
	v_pk_fma_f32 v[68:69], v[68:69], v[146:147], v[128:129]
	v_pk_fma_f32 v[62:63], v[62:63], v[144:145], v[170:171]
	v_pk_fma_f32 v[64:65], v[64:65], v[142:143], v[172:173]
	v_cvt_pk_bf16_f32 v66, v66, v67
	v_cvt_pk_bf16_f32 v67, v68, v69
	v_cvt_pk_bf16_f32 v68, v62, v63
	v_cvt_pk_bf16_f32 v69, v64, v65
	global_store_dwordx4 v[2:3], v[66:69], off
	s_waitcnt vmcnt(21)
	v_pk_fma_f32 v[58:59], v[58:59], v[140:141], v[184:185]
	v_pk_fma_f32 v[60:61], v[60:61], v[138:139], v[186:187]
	v_pk_fma_f32 v[54:55], v[54:55], v[136:137], v[118:119]
	v_pk_fma_f32 v[56:57], v[56:57], v[134:135], v[120:121]
	v_cvt_pk_bf16_f32 v58, v58, v59
	v_cvt_pk_bf16_f32 v59, v60, v61
	v_cvt_pk_bf16_f32 v60, v54, v55
	v_cvt_pk_bf16_f32 v61, v56, v57
	global_store_dwordx4 v[2:3], v[58:61], off offset:256
	v_lshl_add_u64 v[2:3], v[2:3], 0, s[4:5]
	s_waitcnt vmcnt(20)
	v_pk_fma_f32 v[50:51], v[50:51], v[148:149], v[188:189]
	v_pk_fma_f32 v[52:53], v[52:53], v[146:147], v[190:191]
	v_pk_fma_f32 v[46:47], v[46:47], v[144:145], v[192:193]
	v_pk_fma_f32 v[48:49], v[48:49], v[142:143], v[194:195]
	v_cvt_pk_bf16_f32 v50, v50, v51
	v_cvt_pk_bf16_f32 v51, v52, v53
	v_cvt_pk_bf16_f32 v52, v46, v47
	v_cvt_pk_bf16_f32 v53, v48, v49
	global_store_dwordx4 v[2:3], v[50:53], off
	s_waitcnt vmcnt(19)
	v_pk_fma_f32 v[42:43], v[42:43], v[140:141], v[110:111]
	v_pk_fma_f32 v[44:45], v[44:45], v[138:139], v[112:113]
	v_pk_fma_f32 v[38:39], v[38:39], v[136:137], v[208:209]
	v_pk_fma_f32 v[40:41], v[40:41], v[134:135], v[210:211]
	v_cvt_pk_bf16_f32 v42, v42, v43
	v_cvt_pk_bf16_f32 v43, v44, v45
	v_cvt_pk_bf16_f32 v44, v38, v39
	v_cvt_pk_bf16_f32 v45, v40, v41
	global_store_dwordx4 v[2:3], v[42:45], off offset:256
	v_lshl_add_u64 v[2:3], v[2:3], 0, s[4:5]
	s_waitcnt vmcnt(18)
	v_pk_fma_f32 v[34:35], v[34:35], v[148:149], v[226:227]
	v_pk_fma_f32 v[36:37], v[36:37], v[146:147], v[228:229]
	v_pk_fma_f32 v[30:31], v[30:31], v[144:145], v[102:103]
	v_pk_fma_f32 v[32:33], v[32:33], v[142:143], v[104:105]
	v_cvt_pk_bf16_f32 v34, v34, v35
	v_cvt_pk_bf16_f32 v35, v36, v37
	v_cvt_pk_bf16_f32 v36, v30, v31
	v_cvt_pk_bf16_f32 v37, v32, v33
	global_store_dwordx4 v[2:3], v[34:37], off
	s_waitcnt vmcnt(17)
	v_pk_fma_f32 v[26:27], v[26:27], v[140:141], v[230:231]
	v_pk_fma_f32 v[28:29], v[28:29], v[138:139], v[232:233]
	v_pk_fma_f32 v[22:23], v[22:23], v[136:137], v[234:235]
	v_pk_fma_f32 v[24:25], v[24:25], v[134:135], v[236:237]
	v_cvt_pk_bf16_f32 v26, v26, v27
	v_cvt_pk_bf16_f32 v27, v28, v29
	v_cvt_pk_bf16_f32 v28, v22, v23
	v_cvt_pk_bf16_f32 v29, v24, v25
	global_store_dwordx4 v[2:3], v[26:29], off offset:256
	v_lshl_add_u64 v[2:3], v[2:3], 0, s[4:5]
	s_waitcnt vmcnt(16)
	v_pk_fma_f32 v[18:19], v[18:19], v[148:149], v[94:95]
	v_pk_fma_f32 v[20:21], v[20:21], v[146:147], v[96:97]
	v_pk_fma_f32 v[14:15], v[14:15], v[144:145], v[238:239]
	v_pk_fma_f32 v[16:17], v[16:17], v[142:143], v[240:241]
	v_cvt_pk_bf16_f32 v18, v18, v19
	v_cvt_pk_bf16_f32 v19, v20, v21
	v_cvt_pk_bf16_f32 v20, v14, v15
	v_cvt_pk_bf16_f32 v21, v16, v17
	global_store_dwordx4 v[2:3], v[18:21], off
	s_waitcnt vmcnt(15)
	v_pk_fma_f32 v[10:11], v[10:11], v[140:141], v[242:243]
	v_pk_fma_f32 v[12:13], v[12:13], v[138:139], v[244:245]
	v_pk_fma_f32 v[6:7], v[6:7], v[136:137], v[86:87]
	v_pk_fma_f32 v[8:9], v[8:9], v[134:135], v[88:89]
	v_cvt_pk_bf16_f32 v10, v10, v11
	v_cvt_pk_bf16_f32 v11, v12, v13
	v_cvt_pk_bf16_f32 v12, v6, v7
	v_cvt_pk_bf16_f32 v13, v8, v9
	s_and_b64 vcc, exec, s[6:7]
	s_mov_b64 s[4:5], -1
	global_store_dwordx4 v[2:3], v[10:13], off offset:256
	s_branch .Lres_epi_tail
; #define PG8_GAS __attribute__((address_space(1)))
; __device__ __forceinline__ unsigned cvtpk(float lo, float hi) { f32x2 v = {lo, hi}; bf16x2_t b = __builtin_convertvector(v, bf16x2_t); return __builtin_bit_cast(unsigned, b); }
; template <class T> __device__ __forceinline__ GAS T* gp(T* p) { return (GAS T*)p; }
;     __device__ __forceinline__ void operator()(const f32x4 (&acc)[2][2][4][2], const Unit& u, int wr, int wc, int fr, int fq) const {
;     ...
;         for (int bj = 0; bj < 2; ++bj)
; #pragma unroll
;             for (int n = 0; n < 2; ++n) gv[bj][n] = (*(const PG8_GAS f32x4*)(gp + col0 + bj * HALF + 4 * n) + 1.0f) * coef;
; #pragma unroll
;         for (int ai = 0; ai < 2; ++ai)
; #pragma unroll
;             for (int m = 0; m < 4; ++m) {
;                 const size_t off = (size_t)(u.pm * BM + ai * HALF + wr * 64 + m * 16 + fr) * 1024 + col0;
; #pragma unroll
;                 for (int bj = 0; bj < 2; ++bj) {
;                     f32x4 b0, b1;
;                     if (basef) { b0 = __builtin_nontemporal_load((const PG8_GAS f32x4*)(basef + off + bj * HALF)); b1 = __builtin_nontemporal_load((const PG8_GAS f32x4*)(basef + off + bj * HALF + 4)); }
;                     else { const u32x4 w = __builtin_nontemporal_load((const PG8_GAS u32x4*)(baseb + off + bj * HALF));
;                         b0 = (f32x4){__uint_as_float(w.x << 16), __uint_as_float(w.x & 0xffff0000u), __uint_as_float(w.y << 16), __uint_as_float(w.y & 0xffff0000u)};
;                         b1 = (f32x4){__uint_as_float(w.z << 16), __uint_as_float(w.z & 0xffff0000u), __uint_as_float(w.w << 16), __uint_as_float(w.w & 0xffff0000u)}; }
;                     const f32x4 o0 = b0 + gv[bj][0] * acc[ai][bj][m][0], o1 = b1 + gv[bj][1] * acc[ai][bj][m][1];
;                     u32x4 w; w.x = cvtpk(o0[0], o0[1]); w.y = cvtpk(o0[2], o0[3]); w.z = cvtpk(o1[0], o1[1]); w.w = cvtpk(o1[2], o1[3]);
;                     __builtin_nontemporal_store(w, (PG8_GAS u32x4*)(out + off + bj * HALF));
.Lres_epi_bf16:
	s_mov_b32 s4, 0x8000
	s_mov_b32 s5, 0
	s_mov_b32 vcc_lo, 0x28000
	s_mov_b32 vcc_hi, 0
	global_load_dwordx4 v[150:153], v[182:183], off nt
	global_load_dwordx4 v[154:157], v[182:183], off offset:256 nt
	v_lshl_add_u64 v[182:183], v[182:183], 0, s[4:5]
	global_load_dwordx4 v[170:173], v[182:183], off nt
	global_load_dwordx4 v[184:187], v[182:183], off offset:256 nt
	v_lshl_add_u64 v[182:183], v[182:183], 0, s[4:5]
	global_load_dwordx4 v[188:191], v[182:183], off nt
	global_load_dwordx4 v[192:195], v[182:183], off offset:256 nt
	v_lshl_add_u64 v[182:183], v[182:183], 0, s[4:5]
	global_load_dwordx4 v[208:211], v[182:183], off nt
	global_load_dwordx4 v[226:229], v[182:183], off offset:256 nt
	v_lshl_add_u64 v[182:183], v[182:183], 0, vcc
	global_load_dwordx4 v[230:233], v[182:183], off nt
	global_load_dwordx4 v[234:237], v[182:183], off offset:256 nt
	v_lshl_add_u64 v[182:183], v[182:183], 0, s[4:5]
	global_load_dwordx4 v[238:241], v[182:183], off nt
	global_load_dwordx4 v[242:245], v[182:183], off offset:256 nt
	v_lshl_add_u64 v[182:183], v[182:183], 0, s[4:5]
	global_load_dwordx4 v[246:249], v[182:183], off nt
	global_load_dwordx4 v[250:253], v[182:183], off offset:256 nt
	v_lshl_add_u64 v[182:183], v[182:183], 0, s[4:5]
	s_waitcnt vmcnt(13)
	v_pk_add_f32 v[148:149], v[148:149], 1.0 op_sel_hi:[1,0]
	v_pk_add_f32 v[180:181], v[146:147], 1.0 op_sel_hi:[1,0]
	v_pk_mul_f32 v[146:147], s[60:61], v[148:149]
	v_pk_mul_f32 v[148:149], s[10:11], v[180:181]
	v_pk_add_f32 v[180:181], v[142:143], 1.0 op_sel_hi:[1,0]
	v_pk_add_f32 v[142:143], v[144:145], 1.0 op_sel_hi:[1,0]
	v_pk_mul_f32 v[144:145], s[10:11], v[180:181]
	v_pk_mul_f32 v[142:143], s[60:61], v[142:143]
	v_pk_add_f32 v[140:141], v[140:141], 1.0 op_sel_hi:[1,0]
	v_pk_add_f32 v[180:181], v[138:139], 1.0 op_sel_hi:[1,0]
	v_pk_mul_f32 v[138:139], s[60:61], v[140:141]
	v_pk_mul_f32 v[140:141], s[10:11], v[180:181]
	v_pk_add_f32 v[180:181], v[134:135], 1.0 op_sel_hi:[1,0]
	v_pk_add_f32 v[134:135], v[136:137], 1.0 op_sel_hi:[1,0]
	v_pk_mul_f32 v[136:137], s[10:11], v[180:181]
	v_pk_mul_f32 v[134:135], s[60:61], v[134:135]
	v_lshlrev_b32_e32 v180, 16, v150
	v_and_b32_e32 v181, 0xffff0000, v150
	v_pk_fma_f32 v[130:131], v[130:131], v[148:149], v[180:181]
	v_lshlrev_b32_e32 v150, 16, v151
	v_and_b32_e32 v151, 0xffff0000, v151
	v_pk_fma_f32 v[132:133], v[132:133], v[146:147], v[150:151]
	v_lshlrev_b32_e32 v180, 16, v152
	v_and_b32_e32 v181, 0xffff0000, v152
	v_pk_fma_f32 v[126:127], v[126:127], v[144:145], v[180:181]
	v_lshlrev_b32_e32 v152, 16, v153
	v_and_b32_e32 v153, 0xffff0000, v153
	v_pk_fma_f32 v[128:129], v[128:129], v[142:143], v[152:153]
	v_cvt_pk_bf16_f32 v130, v130, v131
	v_cvt_pk_bf16_f32 v131, v132, v133
	v_cvt_pk_bf16_f32 v132, v126, v127
	v_cvt_pk_bf16_f32 v133, v128, v129
	global_load_dwordx4 v[150:153], v[182:183], off nt
	global_load_dwordx4 v[126:129], v[182:183], off offset:256 nt
	global_store_dwordx4 v[2:3], v[130:133], off
	s_waitcnt vmcnt(15)
	v_lshlrev_b32_e32 v180, 16, v154
	v_and_b32_e32 v181, 0xffff0000, v154
	v_pk_fma_f32 v[122:123], v[122:123], v[140:141], v[180:181]
	v_lshlrev_b32_e32 v154, 16, v155
	v_and_b32_e32 v155, 0xffff0000, v155
	v_pk_fma_f32 v[124:125], v[124:125], v[138:139], v[154:155]
	v_lshlrev_b32_e32 v180, 16, v156
	v_and_b32_e32 v181, 0xffff0000, v156
	v_pk_fma_f32 v[118:119], v[118:119], v[136:137], v[180:181]
	v_lshlrev_b32_e32 v156, 16, v157
	v_and_b32_e32 v157, 0xffff0000, v157
	v_pk_fma_f32 v[120:121], v[120:121], v[134:135], v[156:157]
	v_cvt_pk_bf16_f32 v122, v122, v123
	v_cvt_pk_bf16_f32 v123, v124, v125
	v_cvt_pk_bf16_f32 v124, v118, v119
	v_cvt_pk_bf16_f32 v125, v120, v121
	global_store_dwordx4 v[2:3], v[122:125], off offset:256
	v_lshl_add_u64 v[2:3], v[2:3], 0, s[4:5]
	s_waitcnt vmcnt(15)
	v_lshlrev_b32_e32 v180, 16, v170
	v_and_b32_e32 v181, 0xffff0000, v170
	v_pk_fma_f32 v[114:115], v[114:115], v[148:149], v[180:181]
	v_lshlrev_b32_e32 v170, 16, v171
	v_and_b32_e32 v171, 0xffff0000, v171
	v_pk_fma_f32 v[116:117], v[116:117], v[146:147], v[170:171]
	v_lshlrev_b32_e32 v180, 16, v172
	v_and_b32_e32 v181, 0xffff0000, v172
	v_pk_fma_f32 v[110:111], v[110:111], v[144:145], v[180:181]
	v_lshlrev_b32_e32 v172, 16, v173
	v_and_b32_e32 v173, 0xffff0000, v173
	v_pk_fma_f32 v[112:113], v[112:113], v[142:143], v[172:173]
	v_cvt_pk_bf16_f32 v114, v114, v115
	v_cvt_pk_bf16_f32 v115, v116, v117
	v_cvt_pk_bf16_f32 v116, v110, v111
	v_cvt_pk_bf16_f32 v117, v112, v113
	global_store_dwordx4 v[2:3], v[114:117], off
	s_waitcnt vmcnt(15)
	v_lshlrev_b32_e32 v180, 16, v184
	v_and_b32_e32 v181, 0xffff0000, v184
	v_pk_fma_f32 v[106:107], v[106:107], v[140:141], v[180:181]
	v_lshlrev_b32_e32 v184, 16, v185
	v_and_b32_e32 v185, 0xffff0000, v185
	v_pk_fma_f32 v[108:109], v[108:109], v[138:139], v[184:185]
	v_lshlrev_b32_e32 v180, 16, v186
	v_and_b32_e32 v181, 0xffff0000, v186
	v_pk_fma_f32 v[102:103], v[102:103], v[136:137], v[180:181]
	v_lshlrev_b32_e32 v186, 16, v187
	v_and_b32_e32 v187, 0xffff0000, v187
	v_pk_fma_f32 v[104:105], v[104:105], v[134:135], v[186:187]
	v_cvt_pk_bf16_f32 v106, v106, v107
	v_cvt_pk_bf16_f32 v107, v108, v109
	v_cvt_pk_bf16_f32 v108, v102, v103
	v_cvt_pk_bf16_f32 v109, v104, v105
	global_store_dwordx4 v[2:3], v[106:109], off offset:256
	v_lshl_add_u64 v[2:3], v[2:3], 0, s[4:5]
	s_waitcnt vmcnt(15)
; #define PG8_GAS __attribute__((address_space(1)))
; __device__ __forceinline__ unsigned cvtpk(float lo, float hi) { f32x2 v = {lo, hi}; bf16x2_t b = __builtin_convertvector(v, bf16x2_t); return __builtin_bit_cast(unsigned, b); }
;     __device__ __forceinline__ void operator()(const f32x4 (&acc)[2][2][4][2], const Unit& u, int wr, int wc, int fr, int fq) const {
;     ...
;                 for (int bj = 0; bj < 2; ++bj) {
;                     f32x4 b0, b1;
;                     if (basef) { b0 = __builtin_nontemporal_load((const PG8_GAS f32x4*)(basef + off + bj * HALF)); b1 = __builtin_nontemporal_load((const PG8_GAS f32x4*)(basef + off + bj * HALF + 4)); }
;                     else { const u32x4 w = __builtin_nontemporal_load((const PG8_GAS u32x4*)(baseb + off + bj * HALF));
;                         b0 = (f32x4){__uint_as_float(w.x << 16), __uint_as_float(w.x & 0xffff0000u), __uint_as_float(w.y << 16), __uint_as_float(w.y & 0xffff0000u)};
;                         b1 = (f32x4){__uint_as_float(w.z << 16), __uint_as_float(w.z & 0xffff0000u), __uint_as_float(w.w << 16), __uint_as_float(w.w & 0xffff0000u)}; }
;                     const f32x4 o0 = b0 + gv[bj][0] * acc[ai][bj][m][0], o1 = b1 + gv[bj][1] * acc[ai][bj][m][1];
;                     u32x4 w; w.x = cvtpk(o0[0], o0[1]); w.y = cvtpk(o0[2], o0[3]); w.z = cvtpk(o1[0], o1[1]); w.w = cvtpk(o1[2], o1[3]);
;                     __builtin_nontemporal_store(w, (PG8_GAS u32x4*)(out + off + bj * HALF));
	v_lshlrev_b32_e32 v180, 16, v188
	v_and_b32_e32 v181, 0xffff0000, v188
	v_pk_fma_f32 v[98:99], v[98:99], v[148:149], v[180:181]
	v_lshlrev_b32_e32 v188, 16, v189
	v_and_b32_e32 v189, 0xffff0000, v189
	v_pk_fma_f32 v[100:101], v[100:101], v[146:147], v[188:189]
	v_lshlrev_b32_e32 v180, 16, v190
	v_and_b32_e32 v181, 0xffff0000, v190
	v_pk_fma_f32 v[94:95], v[94:95], v[144:145], v[180:181]
	v_lshlrev_b32_e32 v190, 16, v191
	v_and_b32_e32 v191, 0xffff0000, v191
	v_pk_fma_f32 v[96:97], v[96:97], v[142:143], v[190:191]
	v_cvt_pk_bf16_f32 v98, v98, v99
	v_cvt_pk_bf16_f32 v99, v100, v101
	v_cvt_pk_bf16_f32 v100, v94, v95
	v_cvt_pk_bf16_f32 v101, v96, v97
	global_store_dwordx4 v[2:3], v[98:101], off
	s_waitcnt vmcnt(15)
	v_lshlrev_b32_e32 v180, 16, v192
	v_and_b32_e32 v181, 0xffff0000, v192
	v_pk_fma_f32 v[90:91], v[90:91], v[140:141], v[180:181]
	v_lshlrev_b32_e32 v192, 16, v193
	v_and_b32_e32 v193, 0xffff0000, v193
	v_pk_fma_f32 v[92:93], v[92:93], v[138:139], v[192:193]
	v_lshlrev_b32_e32 v180, 16, v194
	v_and_b32_e32 v181, 0xffff0000, v194
	v_pk_fma_f32 v[86:87], v[86:87], v[136:137], v[180:181]
	v_lshlrev_b32_e32 v194, 16, v195
	v_and_b32_e32 v195, 0xffff0000, v195
	v_pk_fma_f32 v[88:89], v[88:89], v[134:135], v[194:195]
	v_cvt_pk_bf16_f32 v90, v90, v91
	v_cvt_pk_bf16_f32 v91, v92, v93
	v_cvt_pk_bf16_f32 v92, v86, v87
	v_cvt_pk_bf16_f32 v93, v88, v89
	global_store_dwordx4 v[2:3], v[90:93], off offset:256
	v_lshl_add_u64 v[2:3], v[2:3], 0, s[4:5]
	s_waitcnt vmcnt(15)
	v_lshlrev_b32_e32 v180, 16, v208
	v_and_b32_e32 v181, 0xffff0000, v208
	v_pk_fma_f32 v[82:83], v[82:83], v[148:149], v[180:181]
	v_lshlrev_b32_e32 v208, 16, v209
	v_and_b32_e32 v209, 0xffff0000, v209
	v_pk_fma_f32 v[84:85], v[84:85], v[146:147], v[208:209]
	v_lshlrev_b32_e32 v180, 16, v210
	v_and_b32_e32 v181, 0xffff0000, v210
	v_pk_fma_f32 v[78:79], v[78:79], v[144:145], v[180:181]
	v_lshlrev_b32_e32 v210, 16, v211
	v_and_b32_e32 v211, 0xffff0000, v211
	v_pk_fma_f32 v[80:81], v[80:81], v[142:143], v[210:211]
	v_cvt_pk_bf16_f32 v82, v82, v83
	v_cvt_pk_bf16_f32 v83, v84, v85
	v_cvt_pk_bf16_f32 v84, v78, v79
	v_cvt_pk_bf16_f32 v85, v80, v81
	global_store_dwordx4 v[2:3], v[82:85], off
	s_waitcnt vmcnt(15)
	v_lshlrev_b32_e32 v180, 16, v226
	v_and_b32_e32 v181, 0xffff0000, v226
	v_pk_fma_f32 v[74:75], v[74:75], v[140:141], v[180:181]
	v_lshlrev_b32_e32 v226, 16, v227
	v_and_b32_e32 v227, 0xffff0000, v227
	v_pk_fma_f32 v[76:77], v[76:77], v[138:139], v[226:227]
	v_lshlrev_b32_e32 v180, 16, v228
	v_and_b32_e32 v181, 0xffff0000, v228
	v_pk_fma_f32 v[70:71], v[70:71], v[136:137], v[180:181]
	v_lshlrev_b32_e32 v228, 16, v229
	v_and_b32_e32 v229, 0xffff0000, v229
	v_pk_fma_f32 v[72:73], v[72:73], v[134:135], v[228:229]
	v_cvt_pk_bf16_f32 v74, v74, v75
	v_cvt_pk_bf16_f32 v75, v76, v77
	v_cvt_pk_bf16_f32 v76, v70, v71
	v_cvt_pk_bf16_f32 v77, v72, v73
	global_store_dwordx4 v[2:3], v[74:77], off offset:256
	v_lshl_add_u64 v[2:3], v[2:3], 0, vcc
	s_waitcnt vmcnt(15)
	v_lshlrev_b32_e32 v180, 16, v230
	v_and_b32_e32 v181, 0xffff0000, v230
	v_pk_fma_f32 v[66:67], v[66:67], v[148:149], v[180:181]
	v_lshlrev_b32_e32 v230, 16, v231
	v_and_b32_e32 v231, 0xffff0000, v231
	v_pk_fma_f32 v[68:69], v[68:69], v[146:147], v[230:231]
	v_lshlrev_b32_e32 v180, 16, v232
	v_and_b32_e32 v181, 0xffff0000, v232
	v_pk_fma_f32 v[62:63], v[62:63], v[144:145], v[180:181]
	v_lshlrev_b32_e32 v232, 16, v233
	v_and_b32_e32 v233, 0xffff0000, v233
	v_pk_fma_f32 v[64:65], v[64:65], v[142:143], v[232:233]
	v_cvt_pk_bf16_f32 v66, v66, v67
	v_cvt_pk_bf16_f32 v67, v68, v69
	v_cvt_pk_bf16_f32 v68, v62, v63
	v_cvt_pk_bf16_f32 v69, v64, v65
	global_store_dwordx4 v[2:3], v[66:69], off
	s_waitcnt vmcnt(15)
	v_lshlrev_b32_e32 v180, 16, v234
	v_and_b32_e32 v181, 0xffff0000, v234
	v_pk_fma_f32 v[58:59], v[58:59], v[140:141], v[180:181]
	v_lshlrev_b32_e32 v234, 16, v235
	v_and_b32_e32 v235, 0xffff0000, v235
	v_pk_fma_f32 v[60:61], v[60:61], v[138:139], v[234:235]
	v_lshlrev_b32_e32 v180, 16, v236
	v_and_b32_e32 v181, 0xffff0000, v236
	v_pk_fma_f32 v[54:55], v[54:55], v[136:137], v[180:181]
	v_lshlrev_b32_e32 v236, 16, v237
	v_and_b32_e32 v237, 0xffff0000, v237
	v_pk_fma_f32 v[56:57], v[56:57], v[134:135], v[236:237]
	v_cvt_pk_bf16_f32 v58, v58, v59
	v_cvt_pk_bf16_f32 v59, v60, v61
	v_cvt_pk_bf16_f32 v60, v54, v55
	v_cvt_pk_bf16_f32 v61, v56, v57
	global_store_dwordx4 v[2:3], v[58:61], off offset:256
	v_lshl_add_u64 v[2:3], v[2:3], 0, s[4:5]
	s_waitcnt vmcnt(15)
; #define PG8_GAS __attribute__((address_space(1)))
; __device__ __forceinline__ unsigned cvtpk(float lo, float hi) { f32x2 v = {lo, hi}; bf16x2_t b = __builtin_convertvector(v, bf16x2_t); return __builtin_bit_cast(unsigned, b); }
;     __device__ __forceinline__ void operator()(const f32x4 (&acc)[2][2][4][2], const Unit& u, int wr, int wc, int fr, int fq) const {
;     ...
;                     else { const u32x4 w = __builtin_nontemporal_load((const PG8_GAS u32x4*)(baseb + off + bj * HALF));
;                         b0 = (f32x4){__uint_as_float(w.x << 16), __uint_as_float(w.x & 0xffff0000u), __uint_as_float(w.y << 16), __uint_as_float(w.y & 0xffff0000u)};
;                         b1 = (f32x4){__uint_as_float(w.z << 16), __uint_as_float(w.z & 0xffff0000u), __uint_as_float(w.w << 16), __uint_as_float(w.w & 0xffff0000u)}; }
;                     const f32x4 o0 = b0 + gv[bj][0] * acc[ai][bj][m][0], o1 = b1 + gv[bj][1] * acc[ai][bj][m][1];
;                     u32x4 w; w.x = cvtpk(o0[0], o0[1]); w.y = cvtpk(o0[2], o0[3]); w.z = cvtpk(o1[0], o1[1]); w.w = cvtpk(o1[2], o1[3]);
;                     __builtin_nontemporal_store(w, (PG8_GAS u32x4*)(out + off + bj * HALF));
	v_lshlrev_b32_e32 v180, 16, v238
	v_and_b32_e32 v181, 0xffff0000, v238
	v_pk_fma_f32 v[50:51], v[50:51], v[148:149], v[180:181]
	v_lshlrev_b32_e32 v238, 16, v239
	v_and_b32_e32 v239, 0xffff0000, v239
	v_pk_fma_f32 v[52:53], v[52:53], v[146:147], v[238:239]
	v_lshlrev_b32_e32 v180, 16, v240
	v_and_b32_e32 v181, 0xffff0000, v240
	v_pk_fma_f32 v[46:47], v[46:47], v[144:145], v[180:181]
	v_lshlrev_b32_e32 v240, 16, v241
	v_and_b32_e32 v241, 0xffff0000, v241
	v_pk_fma_f32 v[48:49], v[48:49], v[142:143], v[240:241]
	v_cvt_pk_bf16_f32 v50, v50, v51
	v_cvt_pk_bf16_f32 v51, v52, v53
	v_cvt_pk_bf16_f32 v52, v46, v47
	v_cvt_pk_bf16_f32 v53, v48, v49
	global_store_dwordx4 v[2:3], v[50:53], off
	s_waitcnt vmcnt(15)
	v_lshlrev_b32_e32 v180, 16, v242
	v_and_b32_e32 v181, 0xffff0000, v242
	v_pk_fma_f32 v[42:43], v[42:43], v[140:141], v[180:181]
	v_lshlrev_b32_e32 v242, 16, v243
	v_and_b32_e32 v243, 0xffff0000, v243
	v_pk_fma_f32 v[44:45], v[44:45], v[138:139], v[242:243]
	v_lshlrev_b32_e32 v180, 16, v244
	v_and_b32_e32 v181, 0xffff0000, v244
	v_pk_fma_f32 v[38:39], v[38:39], v[136:137], v[180:181]
	v_lshlrev_b32_e32 v244, 16, v245
	v_and_b32_e32 v245, 0xffff0000, v245
	v_pk_fma_f32 v[40:41], v[40:41], v[134:135], v[244:245]
	v_cvt_pk_bf16_f32 v42, v42, v43
	v_cvt_pk_bf16_f32 v43, v44, v45
	v_cvt_pk_bf16_f32 v44, v38, v39
	v_cvt_pk_bf16_f32 v45, v40, v41
	global_store_dwordx4 v[2:3], v[42:45], off offset:256
	v_lshl_add_u64 v[2:3], v[2:3], 0, s[4:5]
	s_waitcnt vmcnt(15)
	v_lshlrev_b32_e32 v180, 16, v246
	v_and_b32_e32 v181, 0xffff0000, v246
	v_pk_fma_f32 v[34:35], v[34:35], v[148:149], v[180:181]
	v_lshlrev_b32_e32 v246, 16, v247
	v_and_b32_e32 v247, 0xffff0000, v247
	v_pk_fma_f32 v[36:37], v[36:37], v[146:147], v[246:247]
	v_lshlrev_b32_e32 v180, 16, v248
	v_and_b32_e32 v181, 0xffff0000, v248
	v_pk_fma_f32 v[30:31], v[30:31], v[144:145], v[180:181]
	v_lshlrev_b32_e32 v248, 16, v249
	v_and_b32_e32 v249, 0xffff0000, v249
	v_pk_fma_f32 v[32:33], v[32:33], v[142:143], v[248:249]
	v_cvt_pk_bf16_f32 v34, v34, v35
	v_cvt_pk_bf16_f32 v35, v36, v37
	v_cvt_pk_bf16_f32 v36, v30, v31
	v_cvt_pk_bf16_f32 v37, v32, v33
	global_store_dwordx4 v[2:3], v[34:37], off
	s_waitcnt vmcnt(15)
	v_lshlrev_b32_e32 v180, 16, v250
	v_and_b32_e32 v181, 0xffff0000, v250
	v_pk_fma_f32 v[26:27], v[26:27], v[140:141], v[180:181]
	v_lshlrev_b32_e32 v250, 16, v251
	v_and_b32_e32 v251, 0xffff0000, v251
	v_pk_fma_f32 v[28:29], v[28:29], v[138:139], v[250:251]
	v_lshlrev_b32_e32 v180, 16, v252
	v_and_b32_e32 v181, 0xffff0000, v252
	v_pk_fma_f32 v[22:23], v[22:23], v[136:137], v[180:181]
	v_lshlrev_b32_e32 v252, 16, v253
	v_and_b32_e32 v253, 0xffff0000, v253
	v_pk_fma_f32 v[24:25], v[24:25], v[134:135], v[252:253]
	v_cvt_pk_bf16_f32 v26, v26, v27
	v_cvt_pk_bf16_f32 v27, v28, v29
	v_cvt_pk_bf16_f32 v28, v22, v23
	v_cvt_pk_bf16_f32 v29, v24, v25
	global_store_dwordx4 v[2:3], v[26:29], off offset:256
	v_lshl_add_u64 v[2:3], v[2:3], 0, s[4:5]
	s_waitcnt vmcnt(15)
	v_lshlrev_b32_e32 v180, 16, v150
	v_and_b32_e32 v181, 0xffff0000, v150
	v_pk_fma_f32 v[18:19], v[18:19], v[148:149], v[180:181]
	v_lshlrev_b32_e32 v150, 16, v151
	v_and_b32_e32 v151, 0xffff0000, v151
	v_pk_fma_f32 v[20:21], v[20:21], v[146:147], v[150:151]
	v_lshlrev_b32_e32 v180, 16, v152
	v_and_b32_e32 v181, 0xffff0000, v152
	v_pk_fma_f32 v[14:15], v[14:15], v[144:145], v[180:181]
	v_lshlrev_b32_e32 v152, 16, v153
	v_and_b32_e32 v153, 0xffff0000, v153
	v_pk_fma_f32 v[16:17], v[16:17], v[142:143], v[152:153]
	v_cvt_pk_bf16_f32 v18, v18, v19
	v_cvt_pk_bf16_f32 v19, v20, v21
	v_cvt_pk_bf16_f32 v20, v14, v15
	v_cvt_pk_bf16_f32 v21, v16, v17
	global_store_dwordx4 v[2:3], v[18:21], off
	s_waitcnt vmcnt(15)
	v_lshlrev_b32_e32 v180, 16, v126
	v_and_b32_e32 v181, 0xffff0000, v126
	v_pk_fma_f32 v[10:11], v[10:11], v[140:141], v[180:181]
	v_lshlrev_b32_e32 v126, 16, v127
	v_and_b32_e32 v127, 0xffff0000, v127
	v_pk_fma_f32 v[12:13], v[12:13], v[138:139], v[126:127]
	v_lshlrev_b32_e32 v180, 16, v128
	v_and_b32_e32 v181, 0xffff0000, v128
	v_pk_fma_f32 v[6:7], v[6:7], v[136:137], v[180:181]
	v_lshlrev_b32_e32 v128, 16, v129
	v_and_b32_e32 v129, 0xffff0000, v129
	v_pk_fma_f32 v[8:9], v[8:9], v[134:135], v[128:129]
	v_cvt_pk_bf16_f32 v10, v10, v11
	v_cvt_pk_bf16_f32 v11, v12, v13
	v_cvt_pk_bf16_f32 v12, v6, v7
	v_cvt_pk_bf16_f32 v13, v8, v9
	s_and_b64 vcc, exec, s[6:7]
	s_mov_b64 s[4:5], -1
	global_store_dwordx4 v[2:3], v[10:13], off offset:256
